# P0 forget-gate weight table in LDS: 80-byte row stride (conflict-free ds_read_b128) instead of 64
# speedup vs baseline: 1.1261x; 1.0206x over previous
; #define LAS __attribute__((address_space(3)))
; __device__ __forceinline__ void p0_phase(const Args& a, LAS unsigned char* lds, int tid, int lane, int wave) {
;     ...
;     LAS float* wfl = (LAS float*)(lds + P0_WFL);
;     { const float* w_in = a.in[8];
;       for (int i = tid; i < 4096; i += 512) { const int col = i >> 2, q = i & 3; *(LAS f32x4*)(wfl + col * 16 + 4 * q) = *(const f32x4*)(w_in + (size_t)col * DIN + NIN + 4 * q); } }
;     __syncthreads();
.LBB0_23:
	v_writelane_b32 v254, s48, 25
	s_mov_b64 s[14:15], s[94:95]
	s_or_b64 exec, exec, s[0:1]
	v_lshrrev_b32_e32 v38, 2, v134
	v_mul_u32_u24_e32 v0, 0x1c10, v38
	v_lshlrev_b32_e32 v0, 2, v0
	v_mov_b32_e32 v1, 0
	v_lshl_add_u64 v[2:3], s[68:69], 0, v[0:1]
	v_lshlrev_b32_e32 v0, 4, v134
	v_and_b32_e32 v0, 48, v0
	v_lshl_add_u64 v[20:21], v[2:3], 0, v[0:1]
	v_add_u32_e32 v2, 0x200, v134
	v_lshrrev_b32_e32 v3, 2, v2
	v_mul_u32_u24_e32 v6, 0x1c10, v3
	v_lshlrev_b32_e32 v6, 2, v6
	v_mov_b32_e32 v7, v1
	v_lshlrev_b32_e32 v8, 4, v2
	v_lshl_add_u64 v[6:7], s[68:69], 0, v[6:7]
	v_and_b32_e32 v32, 48, v8
	v_mov_b32_e32 v33, v1
	v_add_u32_e32 v16, 0x600, v134
	v_lshl_add_u64 v[6:7], v[6:7], 0, v[32:33]
	v_lshrrev_b32_e32 v33, 2, v16
	v_add_co_u32_e32 v4, vcc, 0x7000, v20
	v_mul_u32_u24_e32 v14, 0x1c10, v33
	s_movk_i32 s0, 0x7000
	v_addc_co_u32_e32 v5, vcc, 0, v21, vcc
	v_lshlrev_b32_e32 v14, 2, v14
	v_mov_b32_e32 v15, v1
	v_lshlrev_b32_e32 v16, 4, v16
	v_add_co_u32_e32 v8, vcc, s0, v6
	v_lshl_add_u64 v[14:15], s[68:69], 0, v[14:15]
	v_and_b32_e32 v34, 48, v16
	v_mov_b32_e32 v35, v1
	v_add_u32_e32 v24, 0xa00, v134
	v_addc_co_u32_e32 v9, vcc, 0, v7, vcc
	s_mov_b32 s1, 0x70b000
	v_lshl_add_u64 v[14:15], v[14:15], 0, v[34:35]
	v_lshrrev_b32_e32 v35, 2, v24
	v_add_co_u32_e32 v12, vcc, s1, v20
	v_mul_u32_u24_e32 v22, 0x1c10, v35
	s_nop 0
	v_addc_co_u32_e32 v13, vcc, 0, v21, vcc
	v_lshlrev_b32_e32 v22, 2, v22
	v_mov_b32_e32 v23, v1
	v_lshlrev_b32_e32 v24, 4, v24
	v_add_co_u32_e32 v16, vcc, s0, v14
	v_lshl_add_u64 v[22:23], s[68:69], 0, v[22:23]
	v_and_b32_e32 v36, 48, v24
	v_mov_b32_e32 v37, v1
	v_addc_co_u32_e32 v17, vcc, 0, v15, vcc
	s_mov_b32 s1, 0xe0f000
	v_lshl_add_u64 v[22:23], v[22:23], 0, v[36:37]
	v_or_b32_e32 v37, 0xc00, v134
	v_add_co_u32_e32 v20, vcc, s1, v20
	v_lshrrev_b32_e32 v39, 2, v37
	global_load_dwordx4 v[4:7], v[4:5], off
	s_nop 0
	global_load_dwordx4 v[8:11], v[8:9], off
	v_addc_co_u32_e32 v21, vcc, 0, v21, vcc
	v_mul_u32_u24_e32 v28, 0x1c10, v39
	global_load_dwordx4 v[12:15], v[12:13], off
	s_nop 0
	global_load_dwordx4 v[16:19], v[16:17], off
	v_add_co_u32_e32 v24, vcc, s0, v22
	v_lshlrev_b32_e32 v28, 2, v28
	v_mov_b32_e32 v29, v1
	v_addc_co_u32_e32 v25, vcc, 0, v23, vcc
	v_lshl_add_u64 v[28:29], s[68:69], 0, v[28:29]
	global_load_dwordx4 v[20:23], v[20:21], off
	s_nop 0
	global_load_dwordx4 v[24:27], v[24:25], off
	v_lshl_add_u64 v[28:29], v[28:29], 0, v[0:1]
	v_add_co_u32_e32 v28, vcc, 0x7000, v28
	v_mul_u32_u24_e32 v38, 0x50, v38
	s_nop 0
	v_addc_co_u32_e32 v29, vcc, 0, v29, vcc
	global_load_dwordx4 v[28:31], v[28:29], off
	s_add_i32 s51, 0, 0
	v_mul_u32_u24_e32 v3, 0x50, v3
	v_add3_u32 v38, s51, v38, v0
	v_add3_u32 v3, s51, v3, v32
	s_movk_i32 s0, 0xe00
	v_cmp_gt_u32_e32 vcc, s0, v37
	s_waitcnt vmcnt(6)
	ds_write_b128 v38, v[4:7]
	s_waitcnt vmcnt(5)
	ds_write_b128 v3, v[8:11]
	s_waitcnt vmcnt(4)
	ds_write_b128 v38, v[12:15] offset:20480
	v_mul_u32_u24_e32 v3, 0x50, v33
	v_add3_u32 v3, s51, v3, v34
	s_waitcnt vmcnt(3)
	ds_write_b128 v3, v[16:19]
	s_waitcnt vmcnt(2)
	ds_write_b128 v38, v[20:23] offset:40960
	v_mul_u32_u24_e32 v3, 0x50, v35
	v_add3_u32 v3, s51, v3, v36
	s_waitcnt vmcnt(1)
	ds_write_b128 v3, v[24:27]
	v_mul_u32_u24_e32 v3, 0x50, v39
	v_add3_u32 v0, s51, v3, v0
	s_waitcnt vmcnt(0)
	ds_write_b128 v0, v[28:31]
	s_and_saveexec_b64 s[0:1], vcc
	s_xor_b64 s[0:1], exec, s[0:1]
	s_cbranch_execz .LBB0_25
	v_add_u32_e32 v3, 0xe00, v134
	v_lshrrev_b32_e32 v8, 2, v3
	v_mul_u32_u24_e32 v0, 0x1c10, v8
	v_lshlrev_b32_e32 v0, 2, v0
	v_lshl_add_u64 v[4:5], s[68:69], 0, v[0:1]
	v_lshlrev_b32_e32 v0, 4, v3
	v_and_b32_e32 v0, 48, v0
	v_lshl_add_u64 v[4:5], v[4:5], 0, v[0:1]
	v_add_co_u32_e32 v4, vcc, 0x7000, v4
	v_mul_u32_u24_e32 v1, 0x50, v8
	s_nop 0
	v_addc_co_u32_e32 v5, vcc, 0, v5, vcc
	global_load_dwordx4 v[4:7], v[4:5], off
	v_add3_u32 v0, s51, v1, v0
	s_waitcnt vmcnt(0)
	ds_write_b128 v0, v[4:7]
; #define LAS __attribute__((address_space(3)))
; __device__ __forceinline__ unsigned cvt_pk_bf16(float lo, float hi) { unsigned r; asm volatile("v_cvt_pk_bf16_f32 %0, %1, %2" : "=v"(r) : "v"(lo), "v"(hi)); return r; }
; __device__ __forceinline__ void p0_phase(const Args& a, LAS unsigned char* lds, int tid, int lane, int wave) {
;     ...
;     LAS float* lf = (LAS float*)(lds + P0_LF);
;     LAS float* sg = (LAS float*)(lds + P0_SEG);
;     const float* gmix = a.in[7]; const float* bfg = a.in[9];
;     float gm[16];
; #pragma unroll
;     for (int j = 0; j < 16; ++j) gm[j] = gmix[lane + 64 * j];
;     bf16_t* XN = (bf16_t*)(ws + WS_XN);
;     for (int c = blockIdx.x; c < 784; c += gridDim.x) {
;         if (c < 272) {
;             for (int i4 = 0; i4 < 2; ++i4) {
;                 float xa[4][16];
; #pragma unroll
;                 for (int u = 0; u < 4; ++u) { const int row = c * 64 + wave * 8 + i4 * 4 + u; const float* xrow = row < MP ? a.in[0] + (size_t)row * D : a.in[1] + (size_t)(row - MP) * D;
; #pragma unroll
;                     for (int j = 0; j < 16; ++j) xa[u][j] = xrow[lane + 64 * j]; }
; #pragma unroll
;                 for (int u = 0; u < 4; ++u) {
;                 const int rl = wave * 8 + i4 * 4 + u, row = c * 64 + rl;
;                 float ss = 0.f;
; #pragma unroll
;                 for (int j = 0; j < 16; ++j) ss += xa[u][j] * xa[u][j];
;                 const float rstd = 1.0f / sqrtf(wave_sum(ss) * (1.f / D) + EPS);
;                 float f[16];
; #pragma unroll
;                 for (int h = 0; h < 16; ++h) f[h] = 0.f;
; #pragma unroll
;                 for (int j = 0; j < 16; ++j) { const float xn = xa[u][j] * rstd * gm[j];
;                     XN[(size_t)row * D + lane + 64 * j] = (bf16_t)(cvt_pk_bf16(xn, 0.f) & 0xffffu);
;                     const LAS f32x4* wp = (const LAS f32x4*)(wfl + (lane + 64 * j) * 16);
; #pragma unroll
;                     for (int q = 0; q < 4; ++q) { const f32x4 w = wp[q]; f[4 * q + 0] += xn * w[0]; f[4 * q + 1] += xn * w[1]; f[4 * q + 2] += xn * w[2]; f[4 * q + 3] += xn * w[3]; } }
.LBB0_25:
	s_or_b64 exec, exec, s[0:1]
	s_cmpk_lt_i32 s44, 0x310
	s_waitcnt lgkmcnt(0)
	s_barrier
	s_cbranch_scc0 .LBB0_53
	v_lshlrev_b32_e32 v1, 2, v132
	v_or_b32_e32 v0, 0x3c0, v134
	global_load_dword v9, v1, s[66:67]
	global_load_dword v34, v1, s[66:67] offset:256
	global_load_dword v35, v1, s[66:67] offset:512
	global_load_dword v36, v1, s[66:67] offset:768
	global_load_dword v37, v1, s[66:67] offset:1024
	global_load_dword v38, v1, s[66:67] offset:1280
	global_load_dword v39, v1, s[66:67] offset:1536
	global_load_dword v40, v1, s[66:67] offset:1792
	v_lshlrev_b32_e32 v3, 2, v0
	global_load_dword v41, v1, s[66:67] offset:2048
	global_load_dword v42, v1, s[66:67] offset:2304
	global_load_dword v43, v1, s[66:67] offset:2560
	global_load_dword v44, v1, s[66:67] offset:2816
	global_load_dword v45, v1, s[66:67] offset:3072
	global_load_dword v46, v1, s[66:67] offset:3328
	global_load_dword v47, v1, s[66:67] offset:3584
	global_load_dword v48, v3, s[66:67]
	v_mov_b32_e32 v5, 0
	s_add_i32 s4, 0, 0x21000
	v_readlane_b32 s0, v254, 21
	v_lshlrev_b32_e32 v4, 1, v132
	v_lshl_add_u32 v50, v2, 2, s4
	s_lshl_b32 s48, s0, 3
	v_lshl_add_u64 v[2:3], s[88:89], 0, v[4:5]
	s_mov_b64 s[0:1], 0x3000000
	v_lshl_add_u64 v[6:7], v[2:3], 0, s[0:1]
	v_and_b32_e32 v52, 15, v134
	v_lshrrev_b32_e32 v19, 4, v134
	s_movk_i32 s0, 0x100
	v_lshlrev_b32_e32 v14, 2, v134
	v_cmp_gt_u32_e64 s[2:3], s0, v134
	v_lshlrev_b32_e32 v2, 8, v19
	v_lshlrev_b32_e32 v4, 2, v52
	s_add_i32 s0, 0, 0x22000
	v_add3_u32 v53, s4, v2, v4
	v_add_u32_e32 v54, s0, v14
	v_add_u32_e32 v55, s0, v4
	s_add_u32 s0, s88, 0x400000
	v_mul_u32_u24_e32 v4, 0x4400, v52
	s_addc_u32 s1, s89, 0
	v_lshlrev_b32_e32 v4, 2, v4
	v_writelane_b32 v254, s0, 26
	v_lshl_add_u64 v[12:13], s[88:89], 0, v[4:5]
	v_and_b32_e32 v4, 0x3f0, v134
	v_writelane_b32 v254, s1, 27
	v_lshl_add_u64 v[12:13], v[12:13], 0, v[4:5]
	s_mov_b64 s[0:1], 0x200000
	v_lshl_add_u64 v[12:13], v[12:13], 0, s[0:1]
	s_add_u32 s0, s88, 0x148000
	s_addc_u32 s1, s89, 0
	v_writelane_b32 v254, s0, 28
	v_mul_u32_u24_e32 v57, 0x50, v132
	v_mov_b32_e32 v133, v5
	v_writelane_b32 v254, s1, 29
	s_add_u32 s0, s88, 0x140000
	s_addc_u32 s1, s89, 0
	v_writelane_b32 v254, s0, 30
	v_and_b32_e32 v1, 16, v134
	v_and_b32_e32 v3, 8, v134
	v_writelane_b32 v254, s1, 31
	s_movk_i32 s0, 0x4f
	v_cmp_lt_u32_e64 s[0:1], s0, v134
	v_and_b32_e32 v17, 4, v134
	v_and_b32_e32 v18, 3, v134
	v_writelane_b32 v254, s0, 32
	v_lshlrev_b32_e32 v2, 2, v19
	v_add_u32_e32 v4, 0x1400, v57
	v_writelane_b32 v254, s1, 33
	s_movk_i32 s0, 0x5f
	v_cmp_lt_u32_e64 s[0:1], s0, v134
	v_add_u32_e32 v20, 0x2800, v57
	v_add_u32_e32 v21, 0x3c00, v57
	v_writelane_b32 v254, s0, 34
	v_add_u32_e32 v22, 0x5000, v57
	v_add_u32_e32 v23, 0x6400, v57
	v_writelane_b32 v254, s1, 35
	s_movk_i32 s0, 0x6f
	v_cmp_lt_u32_e64 s[0:1], s0, v134
	v_add_u32_e32 v24, 0x7800, v57
	v_add_u32_e32 v25, 0x8c00, v57
	v_writelane_b32 v254, s0, 36
	v_add_u32_e32 v26, 0xa000, v57
	v_add_u32_e32 v27, 0xb400, v57
	v_writelane_b32 v254, s1, 37
	s_movk_i32 s0, 0x7f
	v_cmp_lt_u32_e64 s[0:1], s0, v134
	v_mul_u32_u24_e32 v28, 0x50, v0
	v_lshlrev_b32_e32 v58, 2, v0
	v_writelane_b32 v254, s0, 38
	v_add_u32_e32 v0, 0xc800, v57
	v_mov_b32_e32 v15, v5
	v_writelane_b32 v254, s1, 39
	s_movk_i32 s0, 0x8f
	v_cmp_lt_u32_e64 s[0:1], s0, v134
	v_add_u32_e32 v29, 0xdc00, v57
	v_add_u32_e32 v30, 0xf000, v57
	v_writelane_b32 v254, s0, 40
	v_add_u32_e32 v31, 0x10400, v57
	v_add_u32_e32 v32, 0x11800, v57
	v_writelane_b32 v254, s1, 41
	s_movk_i32 s0, 0x9f
	v_cmp_lt_u32_e64 s[0:1], s0, v134
	v_mbcnt_lo_u32_b32 v33, -1, 0
	s_mov_b32 s67, 0
	v_writelane_b32 v254, s0, 42
	v_add_u32_e32 v49, s4, v14
	v_add_u32_e32 v51, s4, v132
	v_writelane_b32 v254, s1, 43
	s_movk_i32 s0, 0xaf
	v_cmp_lt_u32_e64 s[16:17], s0, v134
	s_movk_i32 s0, 0xbf
	v_cmp_lt_u32_e64 s[18:19], s0, v134
	s_movk_i32 s0, 0xcf
	v_cmp_lt_u32_e64 s[20:21], s0, v134
	s_movk_i32 s0, 0xdf
	v_cmp_lt_u32_e64 s[22:23], s0, v134
	s_movk_i32 s0, 0xef
	v_lshrrev_b32_e32 v8, 2, v132
	v_lshl_add_u64 v[10:11], s[70:71], 0, v[132:133]
	v_or_b32_e32 v56, 0xffffef00, v52
	v_cmp_lt_u32_e64 s[24:25], s0, v134
	v_lshl_add_u64 v[14:15], s[60:61], 0, v[14:15]
	s_mov_b32 s49, 0xf800000
	s_mov_b32 s70, 0xbfb8aa3b
	s_mov_b32 s71, 0xb2a5705f
	s_mov_b32 s50, 0x42ce8ed0
	v_lshlrev_b32_e32 v59, 2, v132
	s_mov_b32 s94, 0xc2b17218
	v_mov_b32_e32 v60, 0x358637bd
	s_mov_b32 s95, 0x7f800000
	v_mov_b32_e32 v61, 0x260
	s_mov_b32 s4, 0x3f2aaaab
	v_mov_b32_e32 v62, 0x3ecc95a3
	s_mov_b32 s5, 0x3f317218
	s_mov_b32 s6, 0x33800000
	v_mov_b32_e32 v63, 0x7f800000
	s_mov_b32 s7, 0xc400000
	v_lshlrev_b32_e32 v16, 2, v2
	v_mbcnt_hi_u32_b32 v64, -1, v33
	v_add_u32_e32 v65, s51, v4
	v_add_u32_e32 v66, s51, v20
	v_add_u32_e32 v67, s51, v21
	v_add_u32_e32 v68, s51, v22
	v_add_u32_e32 v69, s51, v23
	v_add_u32_e32 v70, s51, v24
	v_add_u32_e32 v71, s51, v25
	v_add_u32_e32 v72, s51, v26
	v_add_u32_e32 v73, s51, v27
	v_add_u32_e32 v74, s51, v0
	v_add_u32_e32 v75, s51, v29
	v_add_u32_e32 v76, s51, v30
	v_add_u32_e32 v77, s51, v31
	v_add_u32_e32 v78, s51, v32
	v_add_u32_e32 v79, s51, v28
	s_mov_b32 s33, s44
	v_cmp_gt_u32_e64 s[26:27], 32, v132
	v_cmp_eq_u32_e64 s[28:29], 0, v1
	v_cmp_eq_u32_e64 s[30:31], 0, v3
	v_cmp_eq_u32_e64 s[34:35], 0, v17
	v_cmp_eq_u32_e64 s[36:37], 0, v18
	v_cmp_eq_u32_e64 s[38:39], 15, v19
	v_cmp_gt_u32_e64 s[40:41], 16, v134
	v_cmp_lt_u32_e64 s[42:43], 31, v134
	v_cmp_lt_u32_e64 s[8:9], 47, v134
	v_cmp_lt_u32_e64 s[46:47], 63, v134
	s_branch .LBB0_28
